# pool_diff fast path for full-window prompt rows: 30 row loads issued together
# speedup vs baseline: 1.0147x; 1.0125x over previous
; __device__ __forceinline__ f32x4 unpack4(const u32x2& x) { return (f32x4){bf2f(x.x & 0xffffu), __uint_as_float(x.x & 0xffff0000u), bf2f(x.y & 0xffffu), __uint_as_float(x.y & 0xffff0000u)}; }
; template <int W>
; __device__ __forceinline__ void pool_diff_load(const bf16_t* P, const float* spool, int m, int c0, f32x4 (&v)[W]) {
;     if (m < MPT) {
;         const int s = m & (SEQ - 1);
; #pragma unroll
;         for (int j = 0; j < W; ++j) v[j] = (j <= s) ? unpack4(*(const u32x2*)(P + (size_t)(m - j) * NPROJ + C_PU + c0)) : (f32x4){0.f, 0.f, 0.f, 0.f};
;     } else {
; __device__ __forceinline__ void s2_pool_diff(Frame& F, int l) {
;     ...
;     for (int m = F.gw; m < MROWS; m += F.ngw) {
;         f32x4 v2[2], v4[4], v8[8], v16[16];
;         pool_diff_load<2>(P, spool, m, c0, v2); pool_diff_load<4>(P, spool, m, 256 + c0, v4); pool_diff_load<8>(P, spool, m, 512 + c0, v8); pool_diff_load<16>(P, spool, m, 768 + c0, v16);
;         pool_diff_store<2>(D, m, c0, v2); pool_diff_store<4>(D, m, 256 + c0, v4); pool_diff_store<8>(D, m, 512 + c0, v8); pool_diff_store<16>(D, m, 768 + c0, v16);
.LBB0_445:
	s_and_b32 s22, s4, 0xfff
	s_cmp_lt_u32 s22, 15
	s_cbranch_scc1 .Lpd_slow
	s_mov_b32 s22, 0xffff9200
	s_mov_b32 s23, -1
	v_mov_b64_e32 v[142:143], v[138:139]
	global_load_dwordx2 v[144:145], v[142:143], off offset:-1536
	global_load_dwordx2 v[146:147], v[142:143], off offset:-1024
	global_load_dwordx2 v[148:149], v[142:143], off offset:-512
	global_load_dwordx2 v[150:151], v[142:143], off
	v_lshl_add_u64 v[142:143], v[142:143], 0, s[22:23]
	global_load_dwordx2 v[152:153], v[142:143], off offset:-1536
	global_load_dwordx2 v[154:155], v[142:143], off offset:-1024
	global_load_dwordx2 v[156:157], v[142:143], off offset:-512
	global_load_dwordx2 v[158:159], v[142:143], off
	v_lshl_add_u64 v[142:143], v[142:143], 0, s[22:23]
	global_load_dwordx2 v[160:161], v[142:143], off offset:-1024
	global_load_dwordx2 v[162:163], v[142:143], off offset:-512
	global_load_dwordx2 v[164:165], v[142:143], off
	v_lshl_add_u64 v[142:143], v[142:143], 0, s[22:23]
	global_load_dwordx2 v[166:167], v[142:143], off offset:-1024
	global_load_dwordx2 v[168:169], v[142:143], off offset:-512
	global_load_dwordx2 v[170:171], v[142:143], off
	v_lshl_add_u64 v[142:143], v[142:143], 0, s[22:23]
	global_load_dwordx2 v[172:173], v[142:143], off offset:-512
	global_load_dwordx2 v[174:175], v[142:143], off
	v_lshl_add_u64 v[142:143], v[142:143], 0, s[22:23]
	global_load_dwordx2 v[176:177], v[142:143], off offset:-512
	global_load_dwordx2 v[178:179], v[142:143], off
	v_lshl_add_u64 v[142:143], v[142:143], 0, s[22:23]
	global_load_dwordx2 v[180:181], v[142:143], off offset:-512
	global_load_dwordx2 v[182:183], v[142:143], off
	v_lshl_add_u64 v[142:143], v[142:143], 0, s[22:23]
	global_load_dwordx2 v[184:185], v[142:143], off offset:-512
	global_load_dwordx2 v[186:187], v[142:143], off
	v_lshl_add_u64 v[142:143], v[142:143], 0, s[22:23]
	global_load_dwordx2 v[188:189], v[142:143], off
	v_lshl_add_u64 v[142:143], v[142:143], 0, s[22:23]
	global_load_dwordx2 v[190:191], v[142:143], off
	v_lshl_add_u64 v[142:143], v[142:143], 0, s[22:23]
	global_load_dwordx2 v[192:193], v[142:143], off
	v_lshl_add_u64 v[142:143], v[142:143], 0, s[22:23]
	global_load_dwordx2 v[194:195], v[142:143], off
	v_lshl_add_u64 v[142:143], v[142:143], 0, s[22:23]
	global_load_dwordx2 v[206:207], v[142:143], off
	v_lshl_add_u64 v[142:143], v[142:143], 0, s[22:23]
	global_load_dwordx2 v[208:209], v[142:143], off
	v_lshl_add_u64 v[142:143], v[142:143], 0, s[22:23]
	global_load_dwordx2 v[210:211], v[142:143], off
	v_lshl_add_u64 v[142:143], v[142:143], 0, s[22:23]
	global_load_dwordx2 v[212:213], v[142:143], off
	s_waitcnt vmcnt(26)
	v_lshlrev_b32_e32 v6, 16, v144
	v_and_b32_e32 v7, 0xffff0000, v144
	v_lshlrev_b32_e32 v8, 16, v145
	v_and_b32_e32 v9, 0xffff0000, v145
	v_lshlrev_b32_e32 v22, 16, v146
	v_and_b32_e32 v23, 0xffff0000, v146
	v_lshlrev_b32_e32 v24, 16, v147
	v_and_b32_e32 v25, 0xffff0000, v147
	v_lshlrev_b32_e32 v54, 16, v148
	v_and_b32_e32 v55, 0xffff0000, v148
	v_lshlrev_b32_e32 v56, 16, v149
	v_and_b32_e32 v57, 0xffff0000, v149
	v_lshlrev_b32_e32 v120, 16, v150
	v_and_b32_e32 v121, 0xffff0000, v150
	v_lshlrev_b32_e32 v122, 16, v151
	v_and_b32_e32 v123, 0xffff0000, v151
	s_waitcnt vmcnt(22)
	v_lshlrev_b32_e32 v2, 16, v152
	v_and_b32_e32 v3, 0xffff0000, v152
	v_lshlrev_b32_e32 v4, 16, v153
	v_and_b32_e32 v5, 0xffff0000, v153
	v_lshlrev_b32_e32 v10, 16, v154
	v_and_b32_e32 v11, 0xffff0000, v154
	v_lshlrev_b32_e32 v12, 16, v155
	v_and_b32_e32 v13, 0xffff0000, v155
	v_lshlrev_b32_e32 v26, 16, v156
	v_and_b32_e32 v27, 0xffff0000, v156
	v_lshlrev_b32_e32 v28, 16, v157
	v_and_b32_e32 v29, 0xffff0000, v157
	v_lshlrev_b32_e32 v58, 16, v158
	v_and_b32_e32 v59, 0xffff0000, v158
	v_lshlrev_b32_e32 v60, 16, v159
	v_and_b32_e32 v61, 0xffff0000, v159
	s_waitcnt vmcnt(18)
	v_lshlrev_b32_e32 v14, 16, v160
	v_and_b32_e32 v15, 0xffff0000, v160
	v_lshlrev_b32_e32 v16, 16, v161
	v_and_b32_e32 v17, 0xffff0000, v161
	v_lshlrev_b32_e32 v30, 16, v162
	v_and_b32_e32 v31, 0xffff0000, v162
	v_lshlrev_b32_e32 v32, 16, v163
	v_and_b32_e32 v33, 0xffff0000, v163
	v_lshlrev_b32_e32 v62, 16, v164
	v_and_b32_e32 v63, 0xffff0000, v164
	v_lshlrev_b32_e32 v64, 16, v165
	v_and_b32_e32 v65, 0xffff0000, v165
	v_lshlrev_b32_e32 v18, 16, v166
	v_and_b32_e32 v19, 0xffff0000, v166
	v_lshlrev_b32_e32 v20, 16, v167
	v_and_b32_e32 v21, 0xffff0000, v167
	s_waitcnt vmcnt(14)
	v_lshlrev_b32_e32 v34, 16, v168
	v_and_b32_e32 v35, 0xffff0000, v168
	v_lshlrev_b32_e32 v36, 16, v169
	v_and_b32_e32 v37, 0xffff0000, v169
	v_lshlrev_b32_e32 v66, 16, v170
	v_and_b32_e32 v67, 0xffff0000, v170
	v_lshlrev_b32_e32 v68, 16, v171
	v_and_b32_e32 v69, 0xffff0000, v171
	v_lshlrev_b32_e32 v38, 16, v172
	v_and_b32_e32 v39, 0xffff0000, v172
	v_lshlrev_b32_e32 v40, 16, v173
	v_and_b32_e32 v41, 0xffff0000, v173
	v_lshlrev_b32_e32 v70, 16, v174
	v_and_b32_e32 v71, 0xffff0000, v174
	v_lshlrev_b32_e32 v72, 16, v175
	v_and_b32_e32 v73, 0xffff0000, v175
	s_waitcnt vmcnt(10)
	v_lshlrev_b32_e32 v42, 16, v176
	v_and_b32_e32 v43, 0xffff0000, v176
	v_lshlrev_b32_e32 v44, 16, v177
	v_and_b32_e32 v45, 0xffff0000, v177
	v_lshlrev_b32_e32 v74, 16, v178
	v_and_b32_e32 v75, 0xffff0000, v178
	v_lshlrev_b32_e32 v76, 16, v179
	v_and_b32_e32 v77, 0xffff0000, v179
	v_lshlrev_b32_e32 v46, 16, v180
	v_and_b32_e32 v47, 0xffff0000, v180
	v_lshlrev_b32_e32 v48, 16, v181
	v_and_b32_e32 v49, 0xffff0000, v181
	v_lshlrev_b32_e32 v78, 16, v182
	v_and_b32_e32 v79, 0xffff0000, v182
	v_lshlrev_b32_e32 v80, 16, v183
	v_and_b32_e32 v81, 0xffff0000, v183
	s_waitcnt vmcnt(6)
	v_lshlrev_b32_e32 v50, 16, v184
	v_and_b32_e32 v51, 0xffff0000, v184
	v_lshlrev_b32_e32 v52, 16, v185
	v_and_b32_e32 v53, 0xffff0000, v185
	v_lshlrev_b32_e32 v82, 16, v186
	v_and_b32_e32 v83, 0xffff0000, v186
	v_lshlrev_b32_e32 v84, 16, v187
	v_and_b32_e32 v85, 0xffff0000, v187
	v_lshlrev_b32_e32 v86, 16, v188
	v_and_b32_e32 v87, 0xffff0000, v188
	v_lshlrev_b32_e32 v88, 16, v189
	v_and_b32_e32 v89, 0xffff0000, v189
	v_lshlrev_b32_e32 v90, 16, v190
	v_and_b32_e32 v91, 0xffff0000, v190
	v_lshlrev_b32_e32 v92, 16, v191
	v_and_b32_e32 v93, 0xffff0000, v191
	s_waitcnt vmcnt(2)
	v_lshlrev_b32_e32 v94, 16, v192
	v_and_b32_e32 v95, 0xffff0000, v192
	v_lshlrev_b32_e32 v96, 16, v193
	v_and_b32_e32 v97, 0xffff0000, v193
	v_lshlrev_b32_e32 v100, 16, v194
	v_and_b32_e32 v101, 0xffff0000, v194
	v_lshlrev_b32_e32 v102, 16, v195
	v_and_b32_e32 v103, 0xffff0000, v195
	v_lshlrev_b32_e32 v104, 16, v206
	v_and_b32_e32 v105, 0xffff0000, v206
	v_lshlrev_b32_e32 v106, 16, v207
	v_and_b32_e32 v107, 0xffff0000, v207
	v_lshlrev_b32_e32 v108, 16, v208
	v_and_b32_e32 v109, 0xffff0000, v208
	v_lshlrev_b32_e32 v110, 16, v209
	v_and_b32_e32 v111, 0xffff0000, v209
	s_waitcnt vmcnt(0)
	v_lshlrev_b32_e32 v112, 16, v210
	v_and_b32_e32 v113, 0xffff0000, v210
	v_lshlrev_b32_e32 v114, 16, v211
	v_and_b32_e32 v115, 0xffff0000, v211
	v_lshlrev_b32_e32 v116, 16, v212
	v_and_b32_e32 v117, 0xffff0000, v212
	v_lshlrev_b32_e32 v118, 16, v213
	v_and_b32_e32 v119, 0xffff0000, v213
	s_and_b32 s64, s4, 0xfff
	s_mov_b64 s[22:23], s[44:45]
	s_branch .LBB0_430
